# B loop v6: -m splat QK accumulators, no per-tile row-max pass (overflow caught from tile row sum, redo path), plain f32 row sums, V fragments read once (PV_A and PV_B back to back), one mid-tile align
# speedup vs baseline: 1.0461x; 1.0027x over previous
; DI unsigned cvtpk(float lo, float hi) { f32x2 v = {lo, hi}; bf16x2_t b = __builtin_convertvector(v, bf16x2_t); return __builtin_bit_cast(unsigned, b); }
; DI float fexp2(float x) { return __builtin_amdgcn_exp2f(x); }
; DI float max2f(float a, float b) { float r; asm("v_max_f32_e32 %0, %1, %2" : "=v"(r) : "v"(a), "v"(b)); return r; }
; DI float xhalf_max(float v) { auto rr = __builtin_amdgcn_permlane32_swap(__float_as_uint(v), __float_as_uint(v), false, false); return max2f(__uint_as_float(rr[0]), __uint_as_float(rr[1])); }
; DI void attn_diff_unit(int ub, int Ssh, float lam, float post, const float* subg, const bf16_t* PROJ, bf16_t* O, LAS unsigned char* lds, int wid, int lane) {
;     ...
;         qk64<2, 0>(pa0, pa1, cur, qr, r32, hi);
;         qk64<2, 2>(pb0, pb1, cur, qr, r32, hi);
;         const float mxA = xhalf_max(rowmax32(pa0, pa1)), mxB = xhalf_max(rowmax32(pb0, pb1));
;         if (t == 0 || __any(mxA > mA + 8.0f || mxB > mB + 8.0f)) {
;             const float nA = (t == 0) ? mxA : max2f(mA, mxA), nB = (t == 0) ? mxB : max2f(mB, mxB);
;             const float fA = fexp2(mA - nA), fB = fexp2(mB - nB); mA = nA; mB = nB; lA *= fA; lB *= fB;
; #pragma unroll
;             for (int r = 0; r < 16; ++r) { a0[r] *= fA; a1[r] *= fA; b0[r] *= fB; b1[r] *= fB; }
;         }
;         float sA = 0.f, sB = 0.f;
; #pragma unroll
;         for (int r = 0; r < 16; ++r) { pa0[r] = fexp2(pa0[r] - mA); pa1[r] = fexp2(pa1[r] - mA); sA += pa0[r] + pa1[r]; }
;         pwA[0] = (u32x4){cvtpk(pa0[0], pa0[1]), cvtpk(pa0[2], pa0[3]), cvtpk(pa0[4], pa0[5]), cvtpk(pa0[6], pa0[7])};
;         pwA[1] = (u32x4){cvtpk(pa0[8], pa0[9]), cvtpk(pa0[10], pa0[11]), cvtpk(pa0[12], pa0[13]), cvtpk(pa0[14], pa0[15])};
;         pwA[2] = (u32x4){cvtpk(pa1[0], pa1[1]), cvtpk(pa1[2], pa1[3]), cvtpk(pa1[4], pa1[5]), cvtpk(pa1[6], pa1[7])};
;         pwA[3] = (u32x4){cvtpk(pa1[8], pa1[9]), cvtpk(pa1[10], pa1[11]), cvtpk(pa1[12], pa1[13]), cvtpk(pa1[14], pa1[15])};
.Lbt_nold:
	ds_read_b128 v[82:85], v168
	ds_read_b128 v[86:89], v169
	ds_read_b128 v[98:101], v168 offset:512
	ds_read_b128 v[102:105], v169 offset:512
	ds_read_b128 v[114:117], v200
	ds_read_b128 v[118:121], v201
	ds_read_b128 v[160:163], v200 offset:512
	ds_read_b128 v[164:167], v201 offset:512
	s_waitcnt lgkmcnt(6)
	v_mfma_f32_32x32x16_bf16 v[66:81], v[82:85], v[130:133], v[176:191]
	v_mfma_f32_32x32x16_bf16 v[66:81], v[86:89], v[134:137], v[66:81]
	s_waitcnt lgkmcnt(4)
	v_mfma_f32_32x32x16_bf16 v[82:97], v[98:101], v[130:133], v[176:191]
	v_mfma_f32_32x32x16_bf16 v[82:97], v[102:105], v[134:137], v[82:97]
	s_waitcnt lgkmcnt(2)
	v_mfma_f32_32x32x16_bf16 v[98:113], v[114:117], v[138:141], v[208:223]
	v_mfma_f32_32x32x16_bf16 v[98:113], v[118:121], v[142:145], v[98:113]
	s_waitcnt lgkmcnt(0)
	v_mfma_f32_32x32x16_bf16 v[114:129], v[160:163], v[138:141], v[208:223]
	v_mfma_f32_32x32x16_bf16 v[114:129], v[164:167], v[142:145], v[114:129]
	v_xor_b32_e32 v168, 0x4000, v168
	v_xor_b32_e32 v169, 0x4000, v169
	v_xor_b32_e32 v200, 0x4000, v200
	v_xor_b32_e32 v201, 0x4000, v201
	s_nop 1
	v_exp_f32_e32 v66, v66
	v_exp_f32_e32 v67, v67
	v_exp_f32_e32 v68, v68
	v_exp_f32_e32 v69, v69
	v_exp_f32_e32 v70, v70
	v_exp_f32_e32 v71, v71
	v_mov_b32_e32 v196, v66
	v_mov_b32_e32 v197, v67
	v_cvt_pk_bf16_f32 v66, v66, v67
	v_exp_f32_e32 v72, v72
	v_exp_f32_e32 v73, v73
	v_add_f32_e32 v196, v196, v68
	v_add_f32_e32 v197, v197, v69
	v_cvt_pk_bf16_f32 v67, v68, v69
	v_exp_f32_e32 v74, v74
	v_exp_f32_e32 v75, v75
	v_add_f32_e32 v196, v196, v70
	v_add_f32_e32 v197, v197, v71
	v_cvt_pk_bf16_f32 v68, v70, v71
	v_exp_f32_e32 v76, v76
	v_exp_f32_e32 v77, v77
	v_add_f32_e32 v196, v196, v72
	v_add_f32_e32 v197, v197, v73
	v_cvt_pk_bf16_f32 v69, v72, v73
	v_exp_f32_e32 v78, v78
	v_exp_f32_e32 v79, v79
	v_add_f32_e32 v196, v196, v74
	v_add_f32_e32 v197, v197, v75
	v_cvt_pk_bf16_f32 v70, v74, v75
	v_exp_f32_e32 v80, v80
	v_exp_f32_e32 v81, v81
	v_add_f32_e32 v196, v196, v76
	v_add_f32_e32 v197, v197, v77
	v_cvt_pk_bf16_f32 v71, v76, v77
	v_add_f32_e32 v196, v196, v78
	v_add_f32_e32 v197, v197, v79
	v_cvt_pk_bf16_f32 v72, v78, v79
	v_add_f32_e32 v196, v196, v80
	v_add_f32_e32 v197, v197, v81
	v_cvt_pk_bf16_f32 v73, v80, v81
	v_exp_f32_e32 v82, v82
	v_exp_f32_e32 v83, v83
	v_exp_f32_e32 v84, v84
	v_exp_f32_e32 v85, v85
	v_exp_f32_e32 v86, v86
	v_exp_f32_e32 v87, v87
	v_add_f32_e32 v196, v196, v82
	v_add_f32_e32 v197, v197, v83
	v_cvt_pk_bf16_f32 v82, v82, v83
	v_exp_f32_e32 v88, v88
	v_exp_f32_e32 v89, v89
	v_add_f32_e32 v196, v196, v84
	v_add_f32_e32 v197, v197, v85
	v_cvt_pk_bf16_f32 v83, v84, v85
	v_exp_f32_e32 v90, v90
	v_exp_f32_e32 v91, v91
	v_add_f32_e32 v196, v196, v86
	v_add_f32_e32 v197, v197, v87
	v_cvt_pk_bf16_f32 v84, v86, v87
	v_exp_f32_e32 v92, v92
	v_exp_f32_e32 v93, v93
	v_add_f32_e32 v196, v196, v88
	v_add_f32_e32 v197, v197, v89
	v_cvt_pk_bf16_f32 v85, v88, v89
	v_exp_f32_e32 v94, v94
	v_exp_f32_e32 v95, v95
	v_add_f32_e32 v196, v196, v90
	v_add_f32_e32 v197, v197, v91
	v_cvt_pk_bf16_f32 v86, v90, v91
	v_exp_f32_e32 v96, v96
	v_exp_f32_e32 v97, v97
	v_add_f32_e32 v196, v196, v92
	v_add_f32_e32 v197, v197, v93
	v_cvt_pk_bf16_f32 v87, v92, v93
	v_add_f32_e32 v196, v196, v94
	v_add_f32_e32 v197, v197, v95
	v_cvt_pk_bf16_f32 v88, v94, v95
	v_add_f32_e32 v196, v196, v96
	v_add_f32_e32 v197, v197, v97
	v_cvt_pk_bf16_f32 v89, v96, v97
	v_add_f32_e32 v196, v196, v197
	ds_read_b64_tr_b16 v[74:75], v224 offset:8192
	ds_read_b64_tr_b16 v[76:77], v224 offset:8704
	ds_read_b64_tr_b16 v[78:79], v224 offset:12288
	ds_read_b64_tr_b16 v[80:81], v224 offset:12800
	ds_read_b64_tr_b16 v[90:91], v224 offset:9216
	ds_read_b64_tr_b16 v[92:93], v224 offset:9728
	ds_read_b64_tr_b16 v[94:95], v224 offset:13312
	ds_read_b64_tr_b16 v[96:97], v224 offset:13824
	v_cmp_ngt_f32_e32 vcc, 0x5d800000, v196
	s_cbranch_vccnz .Lbt_redo_a
; DI void attn_diff_unit(int ub, int Ssh, float lam, float post, const float* subg, const bf16_t* PROJ, bf16_t* O, LAS unsigned char* lds, int wid, int lane) {
;     ...
;         for (int ks = 0; ks < 4; ++ks) {
;             const s16x4 lo0 = vtr(vp + ks * 1024), hi0 = vtr(vp + ks * 1024 + 512), lo1 = vtr(vp + 4096 + ks * 1024), hi1 = vtr(vp + 4096 + ks * 1024 + 512);
;             const bf16x8 v0 = (bf16x8){lo0[0], lo0[1], lo0[2], lo0[3], hi0[0], hi0[1], hi0[2], hi0[3]};
;             const bf16x8 v1 = (bf16x8){lo1[0], lo1[1], lo1[2], lo1[3], hi1[0], hi1[1], hi1[2], hi1[3]};
;             const bf16x8 pa = __builtin_bit_cast(bf16x8, pwA[ks]);
;             a0 = __builtin_amdgcn_mfma_f32_32x32x16_bf16(v0, pa, a0, 0, 0, 0);
;             a1 = __builtin_amdgcn_mfma_f32_32x32x16_bf16(v1, pa, a1, 0, 0, 0);
; #pragma unroll
;             for (int r = 4 * ks; r < 4 * ks + 4; ++r) { pb0[r] = fexp2(pb0[r] - mB); pb1[r] = fexp2(pb1[r] - mB); sB += pb0[r] + pb1[r]; }
;         }
;         lA += xhalf_sum(sA); lB += xhalf_sum(sB);
;         pwB[0] = (u32x4){cvtpk(pb0[0], pb0[1]), cvtpk(pb0[2], pb0[3]), cvtpk(pb0[4], pb0[5]), cvtpk(pb0[6], pb0[7])};
;         pwB[1] = (u32x4){cvtpk(pb0[8], pb0[9]), cvtpk(pb0[10], pb0[11]), cvtpk(pb0[12], pb0[13]), cvtpk(pb0[14], pb0[15])};
;         pwB[2] = (u32x4){cvtpk(pb1[0], pb1[1]), cvtpk(pb1[2], pb1[3]), cvtpk(pb1[4], pb1[5]), cvtpk(pb1[6], pb1[7])};
;         pwB[3] = (u32x4){cvtpk(pb1[8], pb1[9]), cvtpk(pb1[10], pb1[11]), cvtpk(pb1[12], pb1[13]), cvtpk(pb1[14], pb1[15])};
; #pragma unroll
;         for (int ks = 0; ks < 4; ++ks) {
;             const s16x4 lo0 = vtr(vp + ks * 1024), hi0 = vtr(vp + ks * 1024 + 512), lo1 = vtr(vp + 4096 + ks * 1024), hi1 = vtr(vp + 4096 + ks * 1024 + 512);
;             const bf16x8 v0 = (bf16x8){lo0[0], lo0[1], lo0[2], lo0[3], hi0[0], hi0[1], hi0[2], hi0[3]};
;             const bf16x8 v1 = (bf16x8){lo1[0], lo1[1], lo1[2], lo1[3], hi1[0], hi1[1], hi1[2], hi1[3]};
;             const bf16x8 pb = __builtin_bit_cast(bf16x8, pwB[ks]);
;             b0 = __builtin_amdgcn_mfma_f32_32x32x16_bf16(v0, pb, b0, 0, 0, 0);
;             b1 = __builtin_amdgcn_mfma_f32_32x32x16_bf16(v1, pb, b1, 0, 0, 0);
;         }
;     };
;     for (int t = 0; t < NT; ++t) {
;         LAS unsigned char* cur = lds + (t & 1) * 16384; LAS unsigned char* nxt = lds + ((t + 1) & 1) * 16384;
.Lbt_ok_a:
	v_add_f32_e32 v156, v156, v196
	s_barrier
	v_exp_f32_e32 v98, v98
	v_exp_f32_e32 v99, v99
	v_exp_f32_e32 v100, v100
	v_exp_f32_e32 v101, v101
	v_exp_f32_e32 v102, v102
	v_exp_f32_e32 v103, v103
	v_mov_b32_e32 v192, v98
	v_mov_b32_e32 v193, v99
	v_cvt_pk_bf16_f32 v98, v98, v99
	v_exp_f32_e32 v104, v104
	v_exp_f32_e32 v105, v105
	v_add_f32_e32 v192, v192, v100
	v_add_f32_e32 v193, v193, v101
	v_cvt_pk_bf16_f32 v99, v100, v101
	v_exp_f32_e32 v106, v106
	v_exp_f32_e32 v107, v107
	v_add_f32_e32 v192, v192, v102
	v_add_f32_e32 v193, v193, v103
	v_cvt_pk_bf16_f32 v100, v102, v103
	v_exp_f32_e32 v108, v108
	v_exp_f32_e32 v109, v109
	v_add_f32_e32 v192, v192, v104
	v_add_f32_e32 v193, v193, v105
	v_cvt_pk_bf16_f32 v101, v104, v105
	v_exp_f32_e32 v110, v110
	v_exp_f32_e32 v111, v111
	v_add_f32_e32 v192, v192, v106
	v_add_f32_e32 v193, v193, v107
	v_cvt_pk_bf16_f32 v102, v106, v107
	v_exp_f32_e32 v112, v112
	v_exp_f32_e32 v113, v113
	v_add_f32_e32 v192, v192, v108
	v_add_f32_e32 v193, v193, v109
	v_cvt_pk_bf16_f32 v103, v108, v109
	v_add_f32_e32 v192, v192, v110
	v_add_f32_e32 v193, v193, v111
	v_cvt_pk_bf16_f32 v104, v110, v111
	v_add_f32_e32 v192, v192, v112
	v_add_f32_e32 v193, v193, v113
	v_cvt_pk_bf16_f32 v105, v112, v113
	v_exp_f32_e32 v114, v114
	v_exp_f32_e32 v115, v115
	v_exp_f32_e32 v116, v116
	v_exp_f32_e32 v117, v117
	v_exp_f32_e32 v118, v118
	v_exp_f32_e32 v119, v119
	v_add_f32_e32 v192, v192, v114
	v_add_f32_e32 v193, v193, v115
	v_cvt_pk_bf16_f32 v114, v114, v115
	v_exp_f32_e32 v120, v120
	v_exp_f32_e32 v121, v121
	v_add_f32_e32 v192, v192, v116
	v_add_f32_e32 v193, v193, v117
	v_cvt_pk_bf16_f32 v115, v116, v117
	v_exp_f32_e32 v122, v122
	v_exp_f32_e32 v123, v123
	v_add_f32_e32 v192, v192, v118
	v_add_f32_e32 v193, v193, v119
	v_cvt_pk_bf16_f32 v116, v118, v119
	v_exp_f32_e32 v124, v124
	v_exp_f32_e32 v125, v125
	v_add_f32_e32 v192, v192, v120
	v_add_f32_e32 v193, v193, v121
	v_cvt_pk_bf16_f32 v117, v120, v121
	v_exp_f32_e32 v126, v126
	v_exp_f32_e32 v127, v127
	v_add_f32_e32 v192, v192, v122
	v_add_f32_e32 v193, v193, v123
	v_cvt_pk_bf16_f32 v118, v122, v123
	v_exp_f32_e32 v128, v128
	v_exp_f32_e32 v129, v129
	v_add_f32_e32 v192, v192, v124
	v_add_f32_e32 v193, v193, v125
	v_cvt_pk_bf16_f32 v119, v124, v125
	v_add_f32_e32 v192, v192, v126
	v_add_f32_e32 v193, v193, v127
	v_cvt_pk_bf16_f32 v120, v126, v127
	v_add_f32_e32 v192, v192, v128
	v_add_f32_e32 v193, v193, v129
	v_cvt_pk_bf16_f32 v121, v128, v129
	v_add_f32_e32 v192, v192, v193
	v_cmp_ngt_f32_e32 vcc, 0x5d800000, v192
	s_cbranch_vccnz .Lbt_redo_b
.Lbt_ok_b:
	v_add_f32_e32 v157, v157, v192
	s_waitcnt lgkmcnt(0)
	v_mfma_f32_32x32x16_bf16 v[34:49], v[74:77], v[66:69], v[34:49]
	v_mfma_f32_32x32x16_bf16 v[2:17], v[78:81], v[66:69], v[2:17]
	v_mfma_f32_32x32x16_bf16 v[50:65], v[74:77], v[98:101], v[50:65]
	v_mfma_f32_32x32x16_bf16 v[18:33], v[78:81], v[98:101], v[18:33]
	ds_read_b64_tr_b16 v[74:75], v224 offset:10240
	ds_read_b64_tr_b16 v[76:77], v224 offset:10752
	ds_read_b64_tr_b16 v[78:79], v224 offset:14336
	ds_read_b64_tr_b16 v[80:81], v224 offset:14848
	v_mfma_f32_32x32x16_bf16 v[34:49], v[90:93], v[70:73], v[34:49]
	v_mfma_f32_32x32x16_bf16 v[2:17], v[94:97], v[70:73], v[2:17]
	v_mfma_f32_32x32x16_bf16 v[50:65], v[90:93], v[102:105], v[50:65]
	v_mfma_f32_32x32x16_bf16 v[18:33], v[94:97], v[102:105], v[18:33]
	ds_read_b64_tr_b16 v[90:91], v224 offset:11264
	ds_read_b64_tr_b16 v[92:93], v224 offset:11776
	ds_read_b64_tr_b16 v[94:95], v224 offset:15360
	ds_read_b64_tr_b16 v[96:97], v224 offset:15872
	s_waitcnt lgkmcnt(4)
	v_mfma_f32_32x32x16_bf16 v[34:49], v[74:77], v[82:85], v[34:49]
	v_mfma_f32_32x32x16_bf16 v[2:17], v[78:81], v[82:85], v[2:17]
	v_mfma_f32_32x32x16_bf16 v[50:65], v[74:77], v[114:117], v[50:65]
	v_mfma_f32_32x32x16_bf16 v[18:33], v[78:81], v[114:117], v[18:33]
	s_waitcnt lgkmcnt(0)
	v_mfma_f32_32x32x16_bf16 v[34:49], v[90:93], v[86:89], v[34:49]
	v_mfma_f32_32x32x16_bf16 v[2:17], v[94:97], v[86:89], v[2:17]
	v_mfma_f32_32x32x16_bf16 v[50:65], v[90:93], v[118:121], v[50:65]
	v_mfma_f32_32x32x16_bf16 v[18:33], v[94:97], v[118:121], v[18:33]
	s_andn2_b64 vcc, exec, s[2:3]
	s_cbranch_vccnz .Lbt_nowr
	s_waitcnt vmcnt(1)
	ds_write_b128 v205, v[146:149]
	s_waitcnt vmcnt(0)
	ds_write_b128 v206, v[150:153] offset:8192

; DI unsigned cvtpk(float lo, float hi) { f32x2 v = {lo, hi}; bf16x2_t b = __builtin_convertvector(v, bf16x2_t); return __builtin_bit_cast(unsigned, b); }
; DI float fexp2(float x) { return __builtin_amdgcn_exp2f(x); }
; DI float max2f(float a, float b) { float r; asm("v_max_f32_e32 %0, %1, %2" : "=v"(r) : "v"(a), "v"(b)); return r; }
; DI float xhalf_max(float v) { auto rr = __builtin_amdgcn_permlane32_swap(__float_as_uint(v), __float_as_uint(v), false, false); return max2f(__uint_as_float(rr[0]), __uint_as_float(rr[1])); }
; DI void attn_diff_unit(int ub, int Ssh, float lam, float post, const float* subg, const bf16_t* PROJ, bf16_t* O, LAS unsigned char* lds, int wid, int lane) {
;     ...
;         qk64<2, 0>(pa0, pa1, cur, qr, r32, hi);
;         qk64<2, 2>(pb0, pb1, cur, qr, r32, hi);
;         const float mxA = xhalf_max(rowmax32(pa0, pa1)), mxB = xhalf_max(rowmax32(pb0, pb1));
;         if (t == 0 || __any(mxA > mA + 8.0f || mxB > mB + 8.0f)) {
;             const float nA = (t == 0) ? mxA : max2f(mA, mxA), nB = (t == 0) ? mxB : max2f(mB, mxB);
;             const float fA = fexp2(mA - nA), fB = fexp2(mB - nB); mA = nA; mB = nB; lA *= fA; lB *= fB;
; #pragma unroll
;             for (int r = 0; r < 16; ++r) { a0[r] *= fA; a1[r] *= fA; b0[r] *= fB; b1[r] *= fB; }
;         }
;         float sA = 0.f, sB = 0.f;
; #pragma unroll
;         for (int r = 0; r < 16; ++r) { pa0[r] = fexp2(pa0[r] - mA); pa1[r] = fexp2(pa1[r] - mA); sA += pa0[r] + pa1[r]; }
;         pwA[0] = (u32x4){cvtpk(pa0[0], pa0[1]), cvtpk(pa0[2], pa0[3]), cvtpk(pa0[4], pa0[5]), cvtpk(pa0[6], pa0[7])};
;         pwA[1] = (u32x4){cvtpk(pa0[8], pa0[9]), cvtpk(pa0[10], pa0[11]), cvtpk(pa0[12], pa0[13]), cvtpk(pa0[14], pa0[15])};
;         pwA[2] = (u32x4){cvtpk(pa1[0], pa1[1]), cvtpk(pa1[2], pa1[3]), cvtpk(pa1[4], pa1[5]), cvtpk(pa1[6], pa1[7])};
;         pwA[3] = (u32x4){cvtpk(pa1[8], pa1[9]), cvtpk(pa1[10], pa1[11]), cvtpk(pa1[12], pa1[13]), cvtpk(pa1[14], pa1[15])};
.Lbt_redo_a:
	v_xor_b32_e32 v0, 0x4000, v168
	v_xor_b32_e32 v207, 0x4000, v169
	ds_read_b128 v[82:85], v0
	ds_read_b128 v[86:89], v207
	ds_read_b128 v[160:163], v0 offset:512
	ds_read_b128 v[164:167], v207 offset:512
	s_waitcnt lgkmcnt(0)
	v_mfma_f32_32x32x16_bf16 v[66:81], v[82:85], v[130:133], v[176:191]
	v_mfma_f32_32x32x16_bf16 v[66:81], v[86:89], v[134:137], v[66:81]
	v_mfma_f32_32x32x16_bf16 v[82:97], v[160:163], v[130:133], v[176:191]
	v_mfma_f32_32x32x16_bf16 v[82:97], v[164:167], v[134:137], v[82:97]
	s_nop 7
	s_nop 7
	v_max3_f32 v196, v66, v67, v68
	v_max3_f32 v197, v69, v70, v71
	v_max3_f32 v196, v196, v72, v73
	v_max3_f32 v197, v197, v74, v75
	v_max3_f32 v196, v196, v76, v77
	v_max3_f32 v197, v197, v78, v79
	v_max3_f32 v196, v196, v80, v81
	v_max3_f32 v197, v197, v82, v83
	v_max3_f32 v196, v196, v84, v85
	v_max3_f32 v197, v197, v86, v87
	v_max3_f32 v196, v196, v88, v89
	v_max3_f32 v197, v197, v90, v91
	v_max3_f32 v196, v196, v92, v93
	v_max3_f32 v197, v197, v94, v95
	v_max3_f32 v196, v196, v96, v97
	v_max_f32_e32 v196, v196, v197
	v_mov_b32_e32 v197, v196
	s_nop 1
	v_permlane32_swap_b32_e32 v196, v197
	v_max_f32_e32 v196, v196, v197
	v_max_f32_e32 v196, 0, v196
	v_exp_f32_e64 v197, -v196
	v_sub_f32_e32 v176, v176, v196
	v_sub_f32_e32 v177, v177, v196
	v_sub_f32_e32 v178, v178, v196
	v_sub_f32_e32 v179, v179, v196
	v_sub_f32_e32 v180, v180, v196
	v_sub_f32_e32 v181, v181, v196
	v_sub_f32_e32 v182, v182, v196
	v_sub_f32_e32 v183, v183, v196
	v_sub_f32_e32 v184, v184, v196
	v_sub_f32_e32 v185, v185, v196
	v_sub_f32_e32 v186, v186, v196
	v_sub_f32_e32 v187, v187, v196
	v_sub_f32_e32 v188, v188, v196
	v_sub_f32_e32 v189, v189, v196
	v_sub_f32_e32 v190, v190, v196
	v_sub_f32_e32 v191, v191, v196
	v_sub_f32_e32 v66, v66, v196
	v_sub_f32_e32 v67, v67, v196
	v_sub_f32_e32 v68, v68, v196
	v_sub_f32_e32 v69, v69, v196
	v_sub_f32_e32 v70, v70, v196
	v_sub_f32_e32 v71, v71, v196
	v_sub_f32_e32 v72, v72, v196
	v_sub_f32_e32 v73, v73, v196
	v_sub_f32_e32 v74, v74, v196
	v_sub_f32_e32 v75, v75, v196
	v_sub_f32_e32 v76, v76, v196
	v_sub_f32_e32 v77, v77, v196
	v_sub_f32_e32 v78, v78, v196
	v_sub_f32_e32 v79, v79, v196
	v_sub_f32_e32 v80, v80, v196
	v_sub_f32_e32 v81, v81, v196
	v_sub_f32_e32 v82, v82, v196
	v_sub_f32_e32 v83, v83, v196
	v_sub_f32_e32 v84, v84, v196
	v_sub_f32_e32 v85, v85, v196
	v_sub_f32_e32 v86, v86, v196
	v_sub_f32_e32 v87, v87, v196
	v_sub_f32_e32 v88, v88, v196
	v_sub_f32_e32 v89, v89, v196
	v_sub_f32_e32 v90, v90, v196
	v_sub_f32_e32 v91, v91, v196
	v_sub_f32_e32 v92, v92, v196
	v_sub_f32_e32 v93, v93, v196
	v_sub_f32_e32 v94, v94, v196
	v_sub_f32_e32 v95, v95, v196
	v_sub_f32_e32 v96, v96, v196
	v_sub_f32_e32 v97, v97, v196
	v_mul_f32_e32 v156, v156, v197
	v_mul_f32_e32 v34, v34, v197
	v_mul_f32_e32 v35, v35, v197
	v_mul_f32_e32 v36, v36, v197
	v_mul_f32_e32 v37, v37, v197
	v_mul_f32_e32 v38, v38, v197
	v_mul_f32_e32 v39, v39, v197
	v_mul_f32_e32 v40, v40, v197
	v_mul_f32_e32 v41, v41, v197
	v_mul_f32_e32 v42, v42, v197
	v_mul_f32_e32 v43, v43, v197
	v_mul_f32_e32 v44, v44, v197
	v_mul_f32_e32 v45, v45, v197
	v_mul_f32_e32 v46, v46, v197
	v_mul_f32_e32 v47, v47, v197
	v_mul_f32_e32 v48, v48, v197
	v_mul_f32_e32 v49, v49, v197
	v_mul_f32_e32 v2, v2, v197
	v_mul_f32_e32 v3, v3, v197
	v_mul_f32_e32 v4, v4, v197
	v_mul_f32_e32 v5, v5, v197
	v_mul_f32_e32 v6, v6, v197
	v_mul_f32_e32 v7, v7, v197
	v_mul_f32_e32 v8, v8, v197
	v_mul_f32_e32 v9, v9, v197
	v_mul_f32_e32 v10, v10, v197
	v_mul_f32_e32 v11, v11, v197
	v_mul_f32_e32 v12, v12, v197
	v_mul_f32_e32 v13, v13, v197
	v_mul_f32_e32 v14, v14, v197
	v_mul_f32_e32 v15, v15, v197
	v_mul_f32_e32 v16, v16, v197
	v_mul_f32_e32 v17, v17, v197
	s_nop 1
	v_exp_f32_e32 v66, v66
	v_exp_f32_e32 v67, v67
	v_exp_f32_e32 v68, v68
	v_exp_f32_e32 v69, v69
	v_exp_f32_e32 v70, v70
	v_exp_f32_e32 v71, v71
	v_mov_b32_e32 v196, v66
	v_mov_b32_e32 v197, v67
	v_cvt_pk_bf16_f32 v66, v66, v67
	v_exp_f32_e32 v72, v72
	v_exp_f32_e32 v73, v73
	v_add_f32_e32 v196, v196, v68
	v_add_f32_e32 v197, v197, v69
	v_cvt_pk_bf16_f32 v67, v68, v69
	v_exp_f32_e32 v74, v74
	v_exp_f32_e32 v75, v75
	v_add_f32_e32 v196, v196, v70
	v_add_f32_e32 v197, v197, v71
	v_cvt_pk_bf16_f32 v68, v70, v71
	v_exp_f32_e32 v76, v76
	v_exp_f32_e32 v77, v77
	v_add_f32_e32 v196, v196, v72
	v_add_f32_e32 v197, v197, v73
	v_cvt_pk_bf16_f32 v69, v72, v73
	v_exp_f32_e32 v78, v78
	v_exp_f32_e32 v79, v79
	v_add_f32_e32 v196, v196, v74
	v_add_f32_e32 v197, v197, v75
	v_cvt_pk_bf16_f32 v70, v74, v75
	v_exp_f32_e32 v80, v80
	v_exp_f32_e32 v81, v81
	v_add_f32_e32 v196, v196, v76
	v_add_f32_e32 v197, v197, v77
	v_cvt_pk_bf16_f32 v71, v76, v77
	v_add_f32_e32 v196, v196, v78
	v_add_f32_e32 v197, v197, v79
	v_cvt_pk_bf16_f32 v72, v78, v79
	v_add_f32_e32 v196, v196, v80
	v_add_f32_e32 v197, v197, v81
	v_cvt_pk_bf16_f32 v73, v80, v81
	v_exp_f32_e32 v82, v82
	v_exp_f32_e32 v83, v83
	v_exp_f32_e32 v84, v84
	v_exp_f32_e32 v85, v85
	v_exp_f32_e32 v86, v86
	v_exp_f32_e32 v87, v87
	v_add_f32_e32 v196, v196, v82
	v_add_f32_e32 v197, v197, v83
	v_cvt_pk_bf16_f32 v82, v82, v83
	v_exp_f32_e32 v88, v88
	v_exp_f32_e32 v89, v89
	v_add_f32_e32 v196, v196, v84
	v_add_f32_e32 v197, v197, v85
	v_cvt_pk_bf16_f32 v83, v84, v85
	v_exp_f32_e32 v90, v90
	v_exp_f32_e32 v91, v91
	v_add_f32_e32 v196, v196, v86
	v_add_f32_e32 v197, v197, v87
	v_cvt_pk_bf16_f32 v84, v86, v87
	v_exp_f32_e32 v92, v92
	v_exp_f32_e32 v93, v93
	v_add_f32_e32 v196, v196, v88
	v_add_f32_e32 v197, v197, v89
	v_cvt_pk_bf16_f32 v85, v88, v89
	v_exp_f32_e32 v94, v94
	v_exp_f32_e32 v95, v95
	v_add_f32_e32 v196, v196, v90
	v_add_f32_e32 v197, v197, v91
	v_cvt_pk_bf16_f32 v86, v90, v91
	v_exp_f32_e32 v96, v96
	v_exp_f32_e32 v97, v97
	v_add_f32_e32 v196, v196, v92
	v_add_f32_e32 v197, v197, v93
	v_cvt_pk_bf16_f32 v87, v92, v93
	v_add_f32_e32 v196, v196, v94
	v_add_f32_e32 v197, v197, v95
	v_cvt_pk_bf16_f32 v88, v94, v95
	v_add_f32_e32 v196, v196, v96
	v_add_f32_e32 v197, v197, v97
	v_cvt_pk_bf16_f32 v89, v96, v97
	v_add_f32_e32 v196, v196, v197
	ds_read_b64_tr_b16 v[74:75], v224 offset:8192
	ds_read_b64_tr_b16 v[76:77], v224 offset:8704
	ds_read_b64_tr_b16 v[78:79], v224 offset:12288
	ds_read_b64_tr_b16 v[80:81], v224 offset:12800
	ds_read_b64_tr_b16 v[90:91], v224 offset:9216
	ds_read_b64_tr_b16 v[92:93], v224 offset:9728
	ds_read_b64_tr_b16 v[94:95], v224 offset:13312
	ds_read_b64_tr_b16 v[96:97], v224 offset:13824
	s_nop 4
	s_branch .Lbt_ok_a
; #define LAS __attribute__((address_space(3)))
; DI void attn_diff_unit(int ub, int Ssh, float lam, float post, const float* subg, const bf16_t* PROJ, bf16_t* O, LAS unsigned char* lds, int wid, int lane) {
;     ...
;         qk64<2, 2>(pb0, pb1, cur, qr, r32, hi);
;         const float mxA = xhalf_max(rowmax32(pa0, pa1)), mxB = xhalf_max(rowmax32(pb0, pb1));
;         if (t == 0 || __any(mxA > mA + 8.0f || mxB > mB + 8.0f)) {
;             const float nA = (t == 0) ? mxA : max2f(mA, mxA), nB = (t == 0) ? mxB : max2f(mB, mxB);
;             const float fA = fexp2(mA - nA), fB = fexp2(mB - nB); mA = nA; mB = nB; lA *= fA; lB *= fB;
; #pragma unroll
;             for (int r = 0; r < 16; ++r) { a0[r] *= fA; a1[r] *= fA; b0[r] *= fB; b1[r] *= fB; }
;         }
;         float sA = 0.f, sB = 0.f;
; #pragma unroll
;         for (int r = 0; r < 16; ++r) { pa0[r] = fexp2(pa0[r] - mA); pa1[r] = fexp2(pa1[r] - mA); sA += pa0[r] + pa1[r]; }
;         pwA[0] = (u32x4){cvtpk(pa0[0], pa0[1]), cvtpk(pa0[2], pa0[3]), cvtpk(pa0[4], pa0[5]), cvtpk(pa0[6], pa0[7])};
;         pwA[1] = (u32x4){cvtpk(pa0[8], pa0[9]), cvtpk(pa0[10], pa0[11]), cvtpk(pa0[12], pa0[13]), cvtpk(pa0[14], pa0[15])};
;         pwA[2] = (u32x4){cvtpk(pa1[0], pa1[1]), cvtpk(pa1[2], pa1[3]), cvtpk(pa1[4], pa1[5]), cvtpk(pa1[6], pa1[7])};
;         pwA[3] = (u32x4){cvtpk(pa1[8], pa1[9]), cvtpk(pa1[10], pa1[11]), cvtpk(pa1[12], pa1[13]), cvtpk(pa1[14], pa1[15])};
;         LAS const unsigned char* vp = cur + 8192 + vlane;
; #pragma unroll
;         for (int ks = 0; ks < 4; ++ks) {
;             const s16x4 lo0 = vtr(vp + ks * 1024), hi0 = vtr(vp + ks * 1024 + 512), lo1 = vtr(vp + 4096 + ks * 1024), hi1 = vtr(vp + 4096 + ks * 1024 + 512);
;             const bf16x8 v0 = (bf16x8){lo0[0], lo0[1], lo0[2], lo0[3], hi0[0], hi0[1], hi0[2], hi0[3]};
;             const bf16x8 v1 = (bf16x8){lo1[0], lo1[1], lo1[2], lo1[3], hi1[0], hi1[1], hi1[2], hi1[3]};
;             const bf16x8 pa = __builtin_bit_cast(bf16x8, pwA[ks]);
;             a0 = __builtin_amdgcn_mfma_f32_32x32x16_bf16(v0, pa, a0, 0, 0, 0);
;             a1 = __builtin_amdgcn_mfma_f32_32x32x16_bf16(v1, pa, a1, 0, 0, 0);
; #pragma unroll
;             for (int r = 4 * ks; r < 4 * ks + 4; ++r) { pb0[r] = fexp2(pb0[r] - mB); pb1[r] = fexp2(pb1[r] - mB); sB += pb0[r] + pb1[r]; }
;         }
;         lA += xhalf_sum(sA); lB += xhalf_sum(sB);
.Lbt_redo_b:
	v_xor_b32_e32 v0, 0x4000, v200
	v_xor_b32_e32 v207, 0x4000, v201
	ds_read_b128 v[114:117], v0
	ds_read_b128 v[118:121], v207
	ds_read_b128 v[160:163], v0 offset:512
	ds_read_b128 v[164:167], v207 offset:512
	s_waitcnt lgkmcnt(0)
	v_mfma_f32_32x32x16_bf16 v[98:113], v[114:117], v[138:141], v[208:223]
	v_mfma_f32_32x32x16_bf16 v[98:113], v[118:121], v[142:145], v[98:113]
	v_mfma_f32_32x32x16_bf16 v[114:129], v[160:163], v[138:141], v[208:223]
	v_mfma_f32_32x32x16_bf16 v[114:129], v[164:167], v[142:145], v[114:129]
	s_nop 7
	s_nop 7
	v_max3_f32 v192, v98, v99, v100
	v_max3_f32 v193, v101, v102, v103
	v_max3_f32 v192, v192, v104, v105
	v_max3_f32 v193, v193, v106, v107
	v_max3_f32 v192, v192, v108, v109
	v_max3_f32 v193, v193, v110, v111
	v_max3_f32 v192, v192, v112, v113
	v_max3_f32 v193, v193, v114, v115
	v_max3_f32 v192, v192, v116, v117
	v_max3_f32 v193, v193, v118, v119
	v_max3_f32 v192, v192, v120, v121
	v_max3_f32 v193, v193, v122, v123
	v_max3_f32 v192, v192, v124, v125
	v_max3_f32 v193, v193, v126, v127
	v_max3_f32 v192, v192, v128, v129
	v_max_f32_e32 v192, v192, v193
	v_mov_b32_e32 v193, v192
	s_nop 1
	v_permlane32_swap_b32_e32 v192, v193
	v_max_f32_e32 v192, v192, v193
	v_max_f32_e32 v192, 0, v192
	v_exp_f32_e64 v193, -v192
	v_sub_f32_e32 v208, v208, v192
	v_sub_f32_e32 v209, v209, v192
	v_sub_f32_e32 v210, v210, v192
	v_sub_f32_e32 v211, v211, v192
	v_sub_f32_e32 v212, v212, v192
	v_sub_f32_e32 v213, v213, v192
	v_sub_f32_e32 v214, v214, v192
	v_sub_f32_e32 v215, v215, v192
	v_sub_f32_e32 v216, v216, v192
	v_sub_f32_e32 v217, v217, v192
	v_sub_f32_e32 v218, v218, v192
	v_sub_f32_e32 v219, v219, v192
	v_sub_f32_e32 v220, v220, v192
	v_sub_f32_e32 v221, v221, v192
	v_sub_f32_e32 v222, v222, v192
	v_sub_f32_e32 v223, v223, v192
	v_sub_f32_e32 v98, v98, v192
	v_sub_f32_e32 v99, v99, v192
	v_sub_f32_e32 v100, v100, v192
	v_sub_f32_e32 v101, v101, v192
	v_sub_f32_e32 v102, v102, v192
	v_sub_f32_e32 v103, v103, v192
	v_sub_f32_e32 v104, v104, v192
	v_sub_f32_e32 v105, v105, v192
	v_sub_f32_e32 v106, v106, v192
	v_sub_f32_e32 v107, v107, v192
	v_sub_f32_e32 v108, v108, v192
	v_sub_f32_e32 v109, v109, v192
	v_sub_f32_e32 v110, v110, v192
	v_sub_f32_e32 v111, v111, v192
	v_sub_f32_e32 v112, v112, v192
	v_sub_f32_e32 v113, v113, v192
	v_sub_f32_e32 v114, v114, v192
	v_sub_f32_e32 v115, v115, v192
	v_sub_f32_e32 v116, v116, v192
	v_sub_f32_e32 v117, v117, v192
	v_sub_f32_e32 v118, v118, v192
	v_sub_f32_e32 v119, v119, v192
	v_sub_f32_e32 v120, v120, v192
	v_sub_f32_e32 v121, v121, v192
	v_sub_f32_e32 v122, v122, v192
	v_sub_f32_e32 v123, v123, v192
	v_sub_f32_e32 v124, v124, v192
	v_sub_f32_e32 v125, v125, v192
	v_sub_f32_e32 v126, v126, v192
	v_sub_f32_e32 v127, v127, v192
	v_sub_f32_e32 v128, v128, v192
	v_sub_f32_e32 v129, v129, v192
	v_mul_f32_e32 v157, v157, v193
	v_mul_f32_e32 v50, v50, v193
	v_mul_f32_e32 v51, v51, v193
	v_mul_f32_e32 v52, v52, v193
	v_mul_f32_e32 v53, v53, v193
	v_mul_f32_e32 v54, v54, v193
	v_mul_f32_e32 v55, v55, v193
	v_mul_f32_e32 v56, v56, v193
	v_mul_f32_e32 v57, v57, v193
	v_mul_f32_e32 v58, v58, v193
	v_mul_f32_e32 v59, v59, v193
	v_mul_f32_e32 v60, v60, v193
	v_mul_f32_e32 v61, v61, v193
	v_mul_f32_e32 v62, v62, v193
	v_mul_f32_e32 v63, v63, v193
	v_mul_f32_e32 v64, v64, v193
	v_mul_f32_e32 v65, v65, v193
	v_mul_f32_e32 v18, v18, v193
	v_mul_f32_e32 v19, v19, v193
	v_mul_f32_e32 v20, v20, v193
	v_mul_f32_e32 v21, v21, v193
	v_mul_f32_e32 v22, v22, v193
	v_mul_f32_e32 v23, v23, v193
	v_mul_f32_e32 v24, v24, v193
	v_mul_f32_e32 v25, v25, v193
	v_mul_f32_e32 v26, v26, v193
	v_mul_f32_e32 v27, v27, v193
	v_mul_f32_e32 v28, v28, v193
	v_mul_f32_e32 v29, v29, v193
	v_mul_f32_e32 v30, v30, v193
	v_mul_f32_e32 v31, v31, v193
	v_mul_f32_e32 v32, v32, v193
	v_mul_f32_e32 v33, v33, v193
	s_nop 1
	v_exp_f32_e32 v98, v98
	v_exp_f32_e32 v99, v99
	v_exp_f32_e32 v100, v100
	v_exp_f32_e32 v101, v101
	v_exp_f32_e32 v102, v102
	v_exp_f32_e32 v103, v103
	v_mov_b32_e32 v192, v98
	v_mov_b32_e32 v193, v99
	v_cvt_pk_bf16_f32 v98, v98, v99
	v_exp_f32_e32 v104, v104
	v_exp_f32_e32 v105, v105
	v_add_f32_e32 v192, v192, v100
	v_add_f32_e32 v193, v193, v101
	v_cvt_pk_bf16_f32 v99, v100, v101
	v_exp_f32_e32 v106, v106
	v_exp_f32_e32 v107, v107
	v_add_f32_e32 v192, v192, v102
	v_add_f32_e32 v193, v193, v103
	v_cvt_pk_bf16_f32 v100, v102, v103
	v_exp_f32_e32 v108, v108
	v_exp_f32_e32 v109, v109
	v_add_f32_e32 v192, v192, v104
	v_add_f32_e32 v193, v193, v105
	v_cvt_pk_bf16_f32 v101, v104, v105
	v_exp_f32_e32 v110, v110
	v_exp_f32_e32 v111, v111
	v_add_f32_e32 v192, v192, v106
	v_add_f32_e32 v193, v193, v107
	v_cvt_pk_bf16_f32 v102, v106, v107
	v_exp_f32_e32 v112, v112
	v_exp_f32_e32 v113, v113
	v_add_f32_e32 v192, v192, v108
	v_add_f32_e32 v193, v193, v109
	v_cvt_pk_bf16_f32 v103, v108, v109
	v_add_f32_e32 v192, v192, v110
	v_add_f32_e32 v193, v193, v111
	v_cvt_pk_bf16_f32 v104, v110, v111
	v_add_f32_e32 v192, v192, v112
	v_add_f32_e32 v193, v193, v113
	v_cvt_pk_bf16_f32 v105, v112, v113
	v_exp_f32_e32 v114, v114
	v_exp_f32_e32 v115, v115
	v_exp_f32_e32 v116, v116
	v_exp_f32_e32 v117, v117
	v_exp_f32_e32 v118, v118
	v_exp_f32_e32 v119, v119
	v_add_f32_e32 v192, v192, v114
	v_add_f32_e32 v193, v193, v115
	v_cvt_pk_bf16_f32 v114, v114, v115
	v_exp_f32_e32 v120, v120
	v_exp_f32_e32 v121, v121
	v_add_f32_e32 v192, v192, v116
	v_add_f32_e32 v193, v193, v117
	v_cvt_pk_bf16_f32 v115, v116, v117
	v_exp_f32_e32 v122, v122
	v_exp_f32_e32 v123, v123
	v_add_f32_e32 v192, v192, v118
	v_add_f32_e32 v193, v193, v119
	v_cvt_pk_bf16_f32 v116, v118, v119
	v_exp_f32_e32 v124, v124
	v_exp_f32_e32 v125, v125
	v_add_f32_e32 v192, v192, v120
	v_add_f32_e32 v193, v193, v121
	v_cvt_pk_bf16_f32 v117, v120, v121
	v_exp_f32_e32 v126, v126
	v_exp_f32_e32 v127, v127
	v_add_f32_e32 v192, v192, v122
	v_add_f32_e32 v193, v193, v123
	v_cvt_pk_bf16_f32 v118, v122, v123
	v_exp_f32_e32 v128, v128
	v_exp_f32_e32 v129, v129
	v_add_f32_e32 v192, v192, v124
	v_add_f32_e32 v193, v193, v125
	v_cvt_pk_bf16_f32 v119, v124, v125
	v_add_f32_e32 v192, v192, v126
	v_add_f32_e32 v193, v193, v127
	v_cvt_pk_bf16_f32 v120, v126, v127
	v_add_f32_e32 v192, v192, v128
	v_add_f32_e32 v193, v193, v129
	v_cvt_pk_bf16_f32 v121, v128, v129
	v_add_f32_e32 v192, v192, v193
	s_nop 4
	s_branch .Lbt_ok_b
